# ss-load hoist in EpiB epilogues; GQA loop: drop dead VALU, cvt into MFMA wait, PV MFMAs interleaved with next-tile sub/exp; real per-half setprio
# speedup vs baseline: 1.0091x; 1.0091x over previous
; #define SLOAD(i, k0) do { sr_[i].vs0 = ld8(&Vh[(long)((k0) + sr) * LDK + sc]); sr_[i].vs1 = ld8(&Vh[(long)((k0) + 32 + sr) * LDK + sc]); \
;     sr_[i].ks0 = ld8(&Kh[(long)((k0) + sr) * LDK + sc]); sr_[i].ks1 = ld8(&Kh[(long)((k0) + 32 + sr) * LDK + sc]); } while (0)
; #define F8_CAT(lo, hi) __builtin_shufflevector(lo, hi, 0, 1, 2, 3, 4, 5, 6, 7)
; #define SLOAD(i, k0) do { sr_[i].ks = *(const i32x4*)(kg + (long)(k0) * LDK); sr_[i].vs = *(const i32x4*)(vg + (k0)); } while (0)
; #define SWRITE(b, i) do { *(i32x4*)(K_lds + (b) * F8_KB + kst) = sr_[i].ks; *(i32x4*)(V_lds + (b) * F8_KB + vst) = sr_[i].vs; } while (0)
; template <int LDQ, int LDK, int LDO, int OSH>
; __device__ __forceinline__ void attn_body_f8(const unsigned char* Qb, const unsigned char* __restrict__ Kh, const unsigned char* __restrict__ VTh, long ldv, unsigned char* Ob, int seq, char* lds) {
;     ...
;   { const unsigned char* Qw = Qb + (long)(wid * QBLK + r32) * LDQ + 32 * hi;
; #pragma unroll
;     for (int j = 0; j < 2; ++j) q8[j] = F8_CAT(*(const i32x4*)(Qw + 64 * j), *(const i32x4*)(Qw + 64 * j + 16)); }
;   const int krow = tid >> 3, kc = tid & 7, kst = krow * 128 + ((kc ^ ((krow >> 1) & 7)) << 4);
;   const int vd = tid >> 2, vc = tid & 3, vst = vd * 64 + ((vc ^ ((vd >> 2) & 3)) << 4);
;   const unsigned char* kg = Kh + (long)krow * LDK + 16 * kc; const unsigned char* vg = VTh + (long)vd * ldv + 16 * vc;
;   struct { i32x4 ks, vs; } sr_[2];
;     ...
;   f32x16 pA0, pA1, pB0, pB1; float mnA, mnB, alA, alB; i32x8 pa; const int NT = seq / KVBLK;
;   if (wid >= 4) __builtin_amdgcn_s_setprio(1);
;   constexpr int SE = 0, SO = 1;
;   SLOAD(SE, 0); asm volatile("s_waitcnt vmcnt(0)" ::: "memory"); SWRITE(0, SE); __syncthreads();
;   qkt8(pA0, pA1, K_lds, q8, r32, hi); partialSM8<5>(pA0, pA1, m_reg, mnA, alA);
; __global__ void __launch_bounds__(NWAVES * 64, 2) mega_fwd(Args args) {
;     ...
;             for (int i = 0; i < nper; ++i) { const int u = vcu * nper + i; if (u >= NU) break;
;                 const int qb = u % nqb; int t = u / nqb; const int gq = t % 4; t /= 4; const int kvh = t % 2, b = t / 2, h = kvh * 4 + gq;
;                 const size_t qoff = ((size_t)b * seq + (size_t)qb * 256) * 1024 + h * 128;
;                 att::attn_body_f8<1024, 256, 1024, OB_SHIFT>(Q8 + qoff, K8 + (size_t)b * seq * 256 + kvh * 128, VT8 + ((size_t)(b * 2 + kvh) * 128) * (size_t)seq, (long)seq, O8B + qoff, seq, (char*)lds);
.LBB0_362:
	v_readlane_b32 s2, v247, 62
	s_add_i32 s8, s50, s2
	s_cmp_ge_i32 s8, s39
	s_mov_b64 s[2:3], -1
	s_cbranch_scc1 .LBB0_361
	s_abs_i32 s3, s8
	s_mul_hi_u32 s9, s3, s51
	s_mul_i32 s10, s9, s38
	s_sub_i32 s3, s3, s10
	s_ashr_i32 s2, s8, 31
	s_add_i32 s10, s9, 1
	s_sub_i32 s11, s3, s38
	s_cmp_ge_u32 s3, s38
	s_cselect_b32 s9, s10, s9
	s_cselect_b32 s3, s11, s3
	s_add_i32 s10, s9, 1
	s_cmp_ge_u32 s3, s38
	s_cselect_b32 s3, s10, s9
	s_xor_b32 s3, s3, s2
	s_sub_i32 s12, s3, s2
	s_mul_i32 s2, s12, s38
	s_ashr_i32 s13, s12, 31
	s_sub_i32 s10, s8, s2
	s_lshr_b32 s2, s13, 29
	s_add_i32 s3, s12, s2
	s_ashr_i32 s2, s3, 3
	s_and_b32 s3, s3, 0x1fffff8
	s_sub_i32 s16, s12, s3
	s_ashr_i32 s3, s2, 31
	v_readlane_b32 s8, v247, 60
	s_lshl_b64 s[8:9], s[2:3], s8
	s_ashr_i32 s11, s10, 31
	s_lshl_b32 s3, s16, 7
	s_lshl_b64 s[10:11], s[10:11], 18
	s_lshl_b64 s[14:15], s[8:9], 10
	s_ashr_i32 s16, s3, 31
	s_add_u32 s3, s10, s3
	v_mov_b32_e32 v60, v214
	s_addc_u32 s10, s11, s16
	s_add_u32 s33, s3, s14
	v_ashrrev_i32_e32 v4, 6, v60
	v_and_b32_e32 v170, 31, v60
	v_lshlrev_b32_e32 v172, 5, v4
	s_addc_u32 s52, s10, s15
	v_or_b32_e32 v2, v172, v170
	s_add_u32 s10, s42, s33
	v_ashrrev_i32_e32 v3, 31, v2
	s_addc_u32 s11, s43, s52
	v_bfe_u32 v171, v60, 5, 1
	v_lshlrev_b64 v[2:3], 10, v[2:3]
	v_lshl_add_u64 v[2:3], s[10:11], 0, v[2:3]
	v_lshlrev_b32_e32 v0, 5, v171
	v_lshl_add_u64 v[2:3], v[2:3], 0, v[0:1]
	global_load_dwordx4 v[126:129], v[2:3], off offset:16
	global_load_dwordx4 v[122:125], v[2:3], off
	global_load_dwordx4 v[118:121], v[2:3], off offset:80
	global_load_dwordx4 v[114:117], v[2:3], off offset:64
	v_cmp_lt_i32_e32 vcc, 3, v4
	s_and_saveexec_b64 s[10:11], vcc
	s_cbranch_execz .Lgqa_prio_skip
	s_setprio 1
.Lgqa_prio_skip:
	s_or_b64 exec, exec, s[10:11]
	s_lshr_b32 s3, s13, 30
	s_add_i32 s12, s12, s3
	s_ashr_i32 s3, s12, 2
	s_lshr_b32 s10, s12, 31
	s_add_i32 s10, s3, s10
	s_and_b32 s10, s10, -2
	s_sub_i32 s3, s3, s10
	s_lshl_b64 s[8:9], s[8:9], 8
	s_add_u32 s12, s44, s8
	s_addc_u32 s13, s45, s9
	s_lshl_b32 s10, s3, 7
	s_ashr_i32 s11, s10, 31
	s_add_u32 s14, s12, s10
	s_addc_u32 s15, s13, s11
	s_lshl_b32 s2, s2, 1
	s_add_i32 s2, s2, s3
	v_and_b32_e32 v0, 0x3fffffc0, v60
	v_ashrrev_i32_e32 v2, 3, v60
	v_lshlrev_b32_e32 v6, 4, v60
	s_ashr_i32 s3, s2, 31
	v_lshl_add_u32 v173, v0, 2, 0
	v_lshlrev_b32_e32 v0, 7, v2
	v_xor_b32_e32 v3, v6, v60
	s_movk_i32 s16, 0x70
	v_ashrrev_i32_e32 v4, 2, v60
	s_lshl_b64 s[2:3], s[2:3], 7
	v_readlane_b32 s18, v247, 60
	v_and_or_b32 v10, v3, s16, v0
	v_lshlrev_b32_e32 v0, 6, v4
	s_lshl_b64 s[12:13], s[2:3], s18
	v_and_or_b32 v11, v3, 48, v0
	v_ashrrev_i32_e32 v3, 31, v2
	s_add_u32 s2, s46, s12
	v_lshlrev_b64 v[50:51], 8, v[2:3]
	v_ashrrev_i32_e32 v5, 31, v4
	s_addc_u32 s3, s47, s13
	v_lshl_add_u64 v[2:3], s[14:15], 0, v[50:51]
	v_and_b32_e32 v0, 0x70, v6
	v_lshlrev_b64 v[52:53], s18, v[4:5]
	v_lshl_add_u64 v[56:57], v[2:3], 0, v[0:1]
	v_lshl_add_u64 v[2:3], s[2:3], 0, v[52:53]
	v_and_b32_e32 v54, 48, v6
	v_mov_b32_e32 v55, v1
	v_lshl_add_u64 v[58:59], v[2:3], 0, v[54:55]
	global_load_dwordx4 v[2:5], v[56:57], off
	global_load_dwordx4 v[6:9], v[58:59], off
	v_add_u32_e32 v225, 0, v10
	s_waitcnt vmcnt(0)
	v_lshlrev_b32_e32 v62, 1, v171
	v_bfe_u32 v63, v60, 1, 3
	v_lshl_add_u32 v61, v170, 7, 0
	v_add_u32_e32 v226, 0, v11
	v_bitop3_b32 v64, v62, v63, 4 bitop3:0x36
	v_lshlrev_b32_e32 v64, 4, v64
	v_add_u32_e32 v230, v61, v64
	s_movk_i32 s2, 0x4000
	s_mov_b32 s16, s17
	s_mov_b32 s18, s17
	s_mov_b32 s19, s17
	s_mov_b32 s20, s17
	s_mov_b32 s21, s17
	s_mov_b32 s22, s17
	s_mov_b32 s23, s17
	s_mov_b32 s24, s17
	s_mov_b32 s25, s17
	s_mov_b32 s26, s17
	s_mov_b32 s27, s17
	s_mov_b32 s28, s17
	s_mov_b32 s29, s17
	s_mov_b32 s30, s17
	s_mov_b32 s31, s17
	s_mov_b32 s35, 4
	v_lshl_add_u32 v229, v170, 2, v173
	v_lshlrev_b32_e32 v228, 4, v171
	s_waitcnt vmcnt(0)
	ds_write_b128 v225, v[2:5]
	v_lshrrev_b32_e32 v2, 1, v60
	v_bitop3_b32 v2, v62, v2, 7 bitop3:0x78
	v_lshlrev_b32_e32 v2, 4, v2
	v_add_u32_e32 v224, v61, v2
	v_bitop3_b32 v2, v62, v63, 1 bitop3:0x36
	v_lshlrev_b32_e32 v2, 4, v2
	v_add_u32_e32 v227, v61, v2
	ds_write_b128 v226, v[6:9] offset:16384
	s_waitcnt lgkmcnt(0)
	s_barrier
	ds_read_b128 v[34:37], v224 offset:4096
	ds_read_b128 v[38:41], v227 offset:4096
	ds_read_b128 v[18:21], v224
	ds_read_b128 v[22:25], v227
	s_waitcnt lgkmcnt(0)
	v_mfma_scale_f32_32x32x64_f8f6f4 v[18:33], v[18:25], v[122:129], 0, v216, v219 op_sel_hi:[0,0,0]
	v_bitop3_b32 v63, v62, v63, 5 bitop3:0x36
	v_lshlrev_b32_e32 v63, 4, v63
	v_add_u32_e32 v233, v61, v63
	ds_read_b128 v[64:67], v230 offset:4096
	ds_read_b128 v[68:71], v233 offset:4096
	ds_read_b128 v[72:75], v230
	ds_read_b128 v[76:79], v233
	v_mov_b64_e32 v[2:3], s[16:17]
	v_mov_b64_e32 v[16:17], s[30:31]
	v_mov_b64_e32 v[4:5], s[18:19]
	v_mov_b64_e32 v[6:7], s[20:21]
	v_mov_b64_e32 v[8:9], s[22:23]
	v_mov_b64_e32 v[10:11], s[24:25]
	v_mov_b64_e32 v[12:13], s[26:27]
	v_mov_b64_e32 v[14:15], s[28:29]
	v_mfma_scale_f32_32x32x64_f8f6f4 v[34:49], v[34:41], v[122:129], 0, v216, v219 op_sel_hi:[0,0,0]
	s_waitcnt lgkmcnt(0)
; #define SLOAD(i, k0) do { sr_[i].vs0 = ld8(&Vh[(long)((k0) + sr) * LDK + sc]); sr_[i].vs1 = ld8(&Vh[(long)((k0) + 32 + sr) * LDK + sc]); \
;     sr_[i].ks0 = ld8(&Kh[(long)((k0) + sr) * LDK + sc]); sr_[i].ks1 = ld8(&Kh[(long)((k0) + 32 + sr) * LDK + sc]); } while (0)
; #define SWRITE(b, i) do { *(bf16x8*)((char*)V_lds + (b) * SHM_V + vst0) = sr_[i].vs0;          \
;     *(bf16x8*)((char*)V_lds + (b) * SHM_V + vst1) = sr_[i].vs1; int kc = sc * 2;               \
;     *(bf16x8*)((char*)K_lds + (b) * SHM_K + KSWZ(sr, kc)) = sr_[i].ks0;                       \
;     *(bf16x8*)((char*)K_lds + (b) * SHM_K + KSWZ(32 + sr, kc)) = sr_[i].ks1; } while (0)
; #define SWAIT() asm volatile("s_waitcnt vmcnt(4)" ::: "memory")
; #define SLOAD(i, k0) do { sr_[i].ks = *(const i32x4*)(kg + (long)(k0) * LDK); sr_[i].vs = *(const i32x4*)(vg + (k0)); } while (0)
; #define SWRITE(b, i) do { *(i32x4*)(K_lds + (b) * F8_KB + kst) = sr_[i].ks; *(i32x4*)(V_lds + (b) * F8_KB + vst) = sr_[i].vs; } while (0)
; #define SWAIT() asm volatile("s_waitcnt vmcnt(2)" ::: "memory")
; template <int THRV>
; __device__ __forceinline__ void partialSM8(f32x16& p0, f32x16& p1, float& m_reg, float& mn, float& alpha) {
;   constexpr float THR2 = (float)THRV * 1.4426950408889634f;
;   float pmax = p0[0];
; #pragma unroll
;   for (int r = 1; r < 16; ++r) pmax = fmaxf(pmax, p0[r]);
; #pragma unroll
;   for (int r = 0; r < 16; ++r) pmax = fmaxf(pmax, p1[r]);
;   { auto rr = __builtin_amdgcn_permlane32_swap(__float_as_uint(pmax), __float_as_uint(pmax), false, false);
;     pmax = fmaxf(__uint_as_float(rr[0]), __uint_as_float(rr[1])); }
;   if (__builtin_expect(__all(pmax - m_reg <= THR2), 1)) { mn = m_reg; alpha = 1.f; }
;   else { mn = fmaxf(m_reg, pmax); alpha = __builtin_amdgcn_exp2f(m_reg - mn); m_reg = mn; }
;   p0 = p0 - mn; p1 = p1 - mn;
; #pragma unroll
;   for (int r = 0; r < 16; ++r) p0[r] = __builtin_amdgcn_exp2f(p0[r]);
; }
; template <int LDQ, int LDK, int LDO, int OSH>
; __device__ __forceinline__ void attn_body_f8(const unsigned char* Qb, const unsigned char* __restrict__ Kh, const unsigned char* __restrict__ VTh, long ldv, unsigned char* Ob, int seq, char* lds) {
;     ...
;   qkt8(pA0, pA1, K_lds, q8, r32, hi); partialSM8<5>(pA0, pA1, m_reg, mnA, alA);
;   SLOAD(SO, KVBLK); if (2 < NT) SLOAD(SE, 2 * KVBLK);
;   SWAIT(); SWRITE(1, SO); __syncthreads();
	v_mfma_scale_f32_32x32x64_f8f6f4 v[18:33], v[72:79], v[114:121], v[18:33], v216, v219 op_sel_hi:[0,0,0]
	v_mfma_scale_f32_32x32x64_f8f6f4 v[34:49], v[64:71], v[114:121], v[34:49], v216, v219 op_sel_hi:[0,0,0]
	s_nop 15
	s_nop 2
	v_max_f32_e32 v63, v19, v19
	v_max_f32_e32 v64, v18, v18
	v_max_f32_e32 v63, v64, v63
	v_max3_f32 v63, v63, v20, v21
	v_max3_f32 v63, v63, v22, v23
	v_max3_f32 v63, v63, v24, v25
	v_max3_f32 v63, v63, v26, v27
	v_max3_f32 v63, v63, v28, v29
	v_max3_f32 v63, v63, v30, v31
	v_max3_f32 v63, v63, v32, v33
	v_max3_f32 v63, v63, v34, v35
	v_max3_f32 v63, v63, v36, v37
	v_max3_f32 v63, v63, v38, v39
	v_max3_f32 v63, v63, v40, v41
	v_max3_f32 v63, v63, v42, v43
	v_max3_f32 v63, v63, v44, v45
	v_max3_f32 v63, v63, v46, v47
	v_max3_f32 v63, v63, v48, v49
	v_mov_b32_e32 v64, v63
	s_nop 1
	v_permlane32_swap_b32_e32 v63, v64
	v_max_f32_e32 v64, v64, v64
	v_max_f32_e32 v63, v63, v63
	v_max_f32_e32 v63, v63, v64
	v_add_f32_e32 v64, 0x7149f2ca, v63
	v_cmp_ge_f32_e32 vcc, s37, v64
	v_add_co_u32_e64 v64, s[2:3], s2, v56
	s_cmp_eq_u64 vcc, exec
	s_nop 0
	v_addc_co_u32_e64 v65, s[2:3], 0, v57, s[2:3]
	s_mov_b32 s2, 0x8000
	s_nop 0
	v_add_co_u32_e64 v56, s[2:3], s2, v56
	global_load_dwordx4 v[64:67], v[64:65], off
	s_nop 0
	global_load_dwordx4 v[68:71], v[58:59], off offset:64
	global_load_dwordx4 v[154:157], v[58:59], off offset:128
	v_addc_co_u32_e64 v57, s[2:3], 0, v57, s[2:3]
	global_load_dwordx4 v[158:161], v[56:57], off
	s_cselect_b64 vcc, -1, 0
	v_max_f32_e32 v56, 0xf149f2ca, v63
	v_cndmask_b32_e32 v208, v56, v220, vcc
	v_sub_f32_e32 v18, v18, v208
	v_sub_f32_e32 v19, v19, v208
	v_exp_f32_e32 v186, v18
	v_lshrrev_b32_e32 v18, 2, v60
	v_sub_f32_e32 v20, v20, v208
	v_exp_f32_e32 v187, v19
	v_bfe_u32 v19, v60, 2, 2
	v_bitop3_b32 v18, v62, v18, 3 bitop3:0x78
	v_sub_f32_e32 v57, 0xf149f2ca, v56
	v_sub_f32_e32 v21, v21, v208
	v_exp_f32_e32 v148, v20
	v_lshlrev_b32_e32 v20, 4, v18
	v_bitop3_b32 v18, v62, v19, 1 bitop3:0x36
	v_exp_f32_e32 v57, v57
	v_sub_f32_e32 v22, v22, v208
	v_exp_f32_e32 v149, v21
	v_lshlrev_b32_e32 v21, 4, v18
	v_lshlrev_b32_e32 v18, 6, v170
	v_sub_f32_e32 v33, v33, v208
	v_sub_f32_e32 v32, v32, v208
	v_sub_f32_e32 v31, v31, v208
	v_sub_f32_e32 v30, v30, v208
	v_sub_f32_e32 v29, v29, v208
	v_sub_f32_e32 v28, v28, v208
	v_sub_f32_e32 v27, v27, v208
	v_sub_f32_e32 v26, v26, v208
	v_sub_f32_e32 v25, v25, v208
	v_sub_f32_e32 v24, v24, v208
	v_sub_f32_e32 v23, v23, v208
	v_exp_f32_e32 v182, v22
	v_sub_u32_e32 v22, v61, v18
	v_lshl_add_u64 v[18:19], v[52:53], 0, s[12:13]
	v_exp_f32_e32 v183, v23
	v_exp_f32_e32 v152, v24
	v_exp_f32_e32 v153, v25
	v_exp_f32_e32 v184, v26
	v_exp_f32_e32 v185, v27
	v_exp_f32_e32 v146, v28
	v_exp_f32_e32 v147, v29
	v_exp_f32_e32 v180, v30
	v_exp_f32_e32 v181, v31
	v_exp_f32_e32 v150, v32
	v_exp_f32_e32 v151, v33
	v_lshl_add_u64 v[174:175], v[18:19], 0, v[54:55]
	v_lshl_add_u64 v[18:19], s[8:9], 0, v[50:51]
	s_waitcnt vmcnt(2)
	v_or_b32_e32 v18, v18, v0
	s_waitcnt vmcnt(3)
	ds_write_b128 v225, v[64:67] offset:8192
	s_waitcnt vmcnt(2)
	ds_write_b128 v226, v[68:71] offset:24576
	v_cndmask_b32_e64 v234, v57, 1.0, vcc
	v_sub_f32_e32 v67, v49, v208
	v_sub_f32_e32 v66, v48, v208
	v_sub_f32_e32 v69, v47, v208
	v_sub_f32_e32 v68, v46, v208
	v_sub_f32_e32 v81, v45, v208
	v_sub_f32_e32 v80, v44, v208
	v_sub_f32_e32 v79, v43, v208
	v_sub_f32_e32 v78, v42, v208
	v_sub_f32_e32 v77, v41, v208
	v_sub_f32_e32 v76, v40, v208
	v_sub_f32_e32 v75, v39, v208
	v_sub_f32_e32 v74, v38, v208
	v_sub_f32_e32 v73, v37, v208
	v_sub_f32_e32 v72, v36, v208
	v_sub_f32_e32 v71, v35, v208
	v_sub_f32_e32 v70, v34, v208
	v_lshl_add_u64 v[176:177], v[18:19], 0, s[10:11]
	v_add_u32_e32 v232, v22, v20
	v_add_u32_e32 v231, v22, v21
	v_mov_b64_e32 v[64:65], v[16:17]
	v_mov_b64_e32 v[48:49], v[16:17]
	v_mov_b64_e32 v[32:33], v[16:17]
	v_cmp_eq_u32_e64 s[2:3], 0, v171
	v_mov_b32_e32 v0, 0
	v_mov_b64_e32 v[62:63], v[14:15]
	v_mov_b64_e32 v[60:61], v[12:13]
	v_mov_b64_e32 v[58:59], v[10:11]
	v_mov_b64_e32 v[56:57], v[8:9]
	v_mov_b64_e32 v[54:55], v[6:7]
	v_mov_b64_e32 v[52:53], v[4:5]
	v_mov_b64_e32 v[50:51], v[2:3]
	v_mov_b64_e32 v[46:47], v[14:15]
	v_mov_b64_e32 v[44:45], v[12:13]
	v_mov_b64_e32 v[42:43], v[10:11]
	v_mov_b64_e32 v[40:41], v[8:9]
	v_mov_b64_e32 v[38:39], v[6:7]
	v_mov_b64_e32 v[36:37], v[4:5]
	v_mov_b64_e32 v[34:35], v[2:3]
	v_mov_b64_e32 v[30:31], v[14:15]
	v_mov_b64_e32 v[28:29], v[12:13]
	v_mov_b64_e32 v[26:27], v[10:11]
	v_mov_b64_e32 v[24:25], v[8:9]
	v_mov_b64_e32 v[22:23], v[6:7]
	v_mov_b64_e32 v[20:21], v[4:5]
	v_mov_b64_e32 v[18:19], v[2:3]
	s_waitcnt lgkmcnt(0)
	s_barrier
; #define F8_MFMA(A, B, C) __builtin_amdgcn_mfma_scale_f32_32x32x64_f8f6f4(A, B, C, 0, 0, 0, 0x7f7f7f7f, 0, 0x7f7f7f7f)
; __device__ __forceinline__ void qkt8(f32x16& p0, f32x16& p1, const char* Ks, const i32x8* q8, int r32, int hi) {
;   const int g = (r32 >> 1) & 7;
;   const char* k0 = Ks + r32 * 128; const char* k1 = k0 + 32 * 128;
; #pragma unroll
;   for (int j = 0; j < 2; ++j) { const int c0 = 4 * j + 2 * hi;
;     const i32x8 a0 = F8_CAT(*(const i32x4*)(k0 + (((c0) ^ g) << 4)), *(const i32x4*)(k0 + (((c0 + 1) ^ g) << 4)));
;     const i32x8 a1 = F8_CAT(*(const i32x4*)(k1 + (((c0) ^ g) << 4)), *(const i32x4*)(k1 + (((c0 + 1) ^ g) << 4)));
;     if (j == 0) { p0 = F8_MFMA_QK(a0, q8[0], f32x16{}); p1 = F8_MFMA_QK(a1, q8[0], f32x16{}); }
;     else { p0 = F8_MFMA_QK(a0, q8[1], p0); p1 = F8_MFMA_QK(a1, q8[1], p1); } }
; }
; __device__ __forceinline__ void pv8(f32x16* o, const char* Vs, i32x8 pa, int r32, int hi) {
; #pragma unroll
;   for (int db = 0; db < 4; ++db) { const int d = 32 * db + r32, f = (d >> 2) & 3; const char* vr = Vs + d * 64;
;     const i32x8 b = F8_CAT(*(const i32x4*)(vr + (((2 * hi) ^ f) << 4)), *(const i32x4*)(vr + (((2 * hi + 1) ^ f) << 4)));
;     o[db] = F8_MFMA(pa, b, o[db]); }
; }
; __device__ __forceinline__ void finishSM8(f32x16& p0, f32x16& p1, float alpha, float& l_reg, i32x8& pa) {
; #pragma unroll
;   for (int r = 0; r < 16; ++r) p1[r] = __builtin_amdgcn_exp2f(p1[r]);
;   float ps;
;   { typedef float f32x8_ __attribute__((ext_vector_type(8)));
;     const f32x16 t = p0 + p1;
;     const f32x8_ t8 = __builtin_shufflevector(t, t, 0, 1, 2, 3, 4, 5, 6, 7) + __builtin_shufflevector(t, t, 8, 9, 10, 11, 12, 13, 14, 15);
;     const f32x4 t4 = __builtin_shufflevector(t8, t8, 0, 1, 2, 3) + __builtin_shufflevector(t8, t8, 4, 5, 6, 7);
;     const f32x2 t2 = __builtin_shufflevector(t4, t4, 0, 1) + __builtin_shufflevector(t4, t4, 2, 3);
;     ps = t2.x + t2.y; }
;   { auto rr = __builtin_amdgcn_permlane32_swap(__float_as_uint(ps), __float_as_uint(ps), false, false);
;     ps = __uint_as_float(rr[0]) + __uint_as_float(rr[1]); }
;   l_reg = l_reg * alpha + ps;
; #pragma unroll
;   for (int w = 0; w < 4; ++w) { pa[w] = (int)pack4_fp8(p0[4 * w], p0[4 * w + 1], p0[4 * w + 2], p0[4 * w + 3]); pa[4 + w] = (int)pack4_fp8(p1[4 * w], p1[4 * w + 1], p1[4 * w + 2], p1[4 * w + 3]); }
; }
.LBB0_366:
	ds_read_b128 v[82:85], v224 offset:8192
	ds_read_b128 v[86:89], v227 offset:8192
	ds_read_b128 v[98:101], v224 offset:12288
	ds_read_b128 v[102:105], v227 offset:12288
	ds_read_b128 v[130:133], v230 offset:12288
	ds_read_b128 v[138:141], v230 offset:8192
	ds_read_b128 v[134:137], v233 offset:12288
	ds_read_b128 v[142:145], v233 offset:8192
	v_exp_f32_e32 v196, v70
	s_waitcnt lgkmcnt(6)
	v_mfma_scale_f32_32x32x64_f8f6f4 v[82:97], v[82:89], v[122:129], 0, v216, v219 op_sel_hi:[0,0,0]
	v_exp_f32_e32 v197, v71
	v_exp_f32_e32 v192, v72
	v_exp_f32_e32 v193, v73
	v_exp_f32_e32 v194, v74
	v_exp_f32_e32 v195, v75
	v_exp_f32_e32 v206, v76
	v_exp_f32_e32 v207, v77
	v_exp_f32_e32 v204, v78
	v_exp_f32_e32 v205, v79
	v_exp_f32_e32 v198, v80
	v_exp_f32_e32 v199, v81
	v_exp_f32_e32 v202, v68
	v_exp_f32_e32 v200, v66
	v_exp_f32_e32 v201, v67
	v_exp_f32_e32 v203, v69
	s_waitcnt lgkmcnt(4)
	v_mfma_scale_f32_32x32x64_f8f6f4 v[98:113], v[98:105], v[122:129], 0, v216, v219 op_sel_hi:[0,0,0]
	v_add_f32_e64 v66, v146, v198
	v_add_f32_e64 v67, v147, v199
	v_add_f32_e64 v68, v148, v192
	v_add_f32_e64 v69, v149, v193
	v_add_f32_e64 v70, v150, v200
	v_add_f32_e64 v71, v151, v201
	v_add_f32_e64 v72, v152, v206
	v_add_f32_e64 v73, v153, v207
	v_add_f32_e64 v74, v184, v204
	v_add_f32_e64 v75, v185, v205
	v_add_f32_e64 v76, v186, v196
	v_add_f32_e64 v77, v187, v197
	v_add_f32_e64 v78, v180, v202
	v_add_f32_e64 v79, v181, v203
	v_pk_add_f32 v[80:81], v[182:183], v[194:195]
	v_pk_add_f32 v[74:75], v[76:77], v[74:75]
	v_pk_add_f32 v[78:79], v[80:81], v[78:79]
	v_pk_add_f32 v[70:71], v[72:73], v[70:71]
	v_pk_add_f32 v[66:67], v[68:69], v[66:67]
	v_pk_add_f32 v[68:69], v[74:75], v[78:79]
	v_pk_add_f32 v[66:67], v[66:67], v[70:71]
	s_waitcnt lgkmcnt(0)
	v_mfma_scale_f32_32x32x64_f8f6f4 v[82:97], v[138:145], v[114:121], v[82:97], v216, v219 op_sel_hi:[0,0,0]
	v_add_f32_e64 v66, v68, v66
	v_add_f32_e64 v67, v69, v67
	v_add_f32_e64 v178, v66, v67
	v_mov_b32_e32 v235, v178
	s_nop 1
	v_permlane32_swap_b32_e32 v178, v235
	v_mfma_scale_f32_32x32x64_f8f6f4 v[98:113], v[130:137], v[114:121], v[98:113], v216, v219 op_sel_hi:[0,0,0]
	v_lshl_add_u64 v[190:191], s[4:5], 0, v[176:177]
	s_mov_b32 s8, 0x1630c000
	v_add_co_u32_e32 v66, vcc, s8, v190
	v_lshl_add_u64 v[188:189], s[4:5], 0, v[174:175]
	s_nop 0
	v_addc_co_u32_e32 v67, vcc, 0, v191, vcc
	s_mov_b32 s8, 0x16b00000
	v_add_co_u32_e32 v68, vcc, s8, v188
	s_nop 1
	v_addc_co_u32_e32 v69, vcc, 0, v189, vcc
	global_load_dwordx4 v[162:165], v[66:67], off
	global_load_dwordx4 v[166:169], v[68:69], off offset:192
	v_max_f32_e32 v179, v82, v83
	v_max3_f32 v179, v179, v84, v85
	v_max3_f32 v179, v179, v86, v87
	v_max3_f32 v179, v179, v88, v89
	v_max3_f32 v179, v179, v90, v91
	v_max3_f32 v179, v179, v92, v93
	v_max3_f32 v179, v179, v94, v95
	v_max3_f32 v179, v179, v96, v97
	v_max3_f32 v179, v179, v98, v99
	v_max3_f32 v179, v179, v100, v101
	v_max3_f32 v179, v179, v102, v103
	s_waitcnt lgkmcnt(0)
	v_max3_f32 v179, v179, v104, v105
	ds_read_b128 v[138:141], v232 offset:16384
	ds_read_b128 v[130:133], v232 offset:18432
	ds_read_b128 v[142:145], v231 offset:16384
	ds_read_b128 v[134:137], v231 offset:18432
	ds_read_b128 v[74:77], v232 offset:20480
	ds_read_b128 v[66:69], v232 offset:22528
	ds_read_b128 v[78:81], v231 offset:20480
	ds_read_b128 v[70:73], v231 offset:22528
	v_max3_f32 v179, v179, v106, v107
	v_max3_f32 v179, v179, v108, v109
	v_max3_f32 v179, v179, v110, v111
	v_max3_f32 v179, v179, v112, v113
	v_mov_b32_e32 v209, v179
	s_nop 1
	v_permlane32_swap_b32_e32 v179, v209
	v_max_f32_e32 v179, v179, v209
	v_sub_f32_e32 v209, v179, v208
	v_cmp_ge_f32_e32 vcc, s37, v209
	s_cmp_lg_u64 vcc, exec
	s_cbranch_scc1 .LBB0_383
	v_mov_b32_e32 v236, v208

; __device__ __forceinline__ unsigned pack4_fp8(float a, float b, float c, float d) { int r = 0; r = __builtin_amdgcn_cvt_pk_fp8_f32(a, b, r, false); r = __builtin_amdgcn_cvt_pk_fp8_f32(c, d, r, true); return (unsigned)r; }
; #define SBAR() __builtin_amdgcn_sched_barrier(0)
; #define SWAIT() asm volatile("s_waitcnt vmcnt(4)" ::: "memory")
; __device__ __forceinline__ void pv8(f32x16* o, const char* Vs, i32x8 pa, int r32, int hi) {
; #pragma unroll
;   for (int db = 0; db < 4; ++db) { const int d = 32 * db + r32, f = (d >> 2) & 3; const char* vr = Vs + d * 64;
;     const i32x8 b = F8_CAT(*(const i32x4*)(vr + (((2 * hi) ^ f) << 4)), *(const i32x4*)(vr + (((2 * hi + 1) ^ f) << 4)));
;     o[db] = F8_MFMA(pa, b, o[db]); }
; }
; __device__ __forceinline__ void finishSM8(f32x16& p0, f32x16& p1, float alpha, float& l_reg, i32x8& pa) {
; #pragma unroll
;   for (int r = 0; r < 16; ++r) p1[r] = __builtin_amdgcn_exp2f(p1[r]);
;   float ps;
;   { typedef float f32x8_ __attribute__((ext_vector_type(8)));
;     const f32x16 t = p0 + p1;
;     const f32x8_ t8 = __builtin_shufflevector(t, t, 0, 1, 2, 3, 4, 5, 6, 7) + __builtin_shufflevector(t, t, 8, 9, 10, 11, 12, 13, 14, 15);
;     const f32x4 t4 = __builtin_shufflevector(t8, t8, 0, 1, 2, 3) + __builtin_shufflevector(t8, t8, 4, 5, 6, 7);
;     const f32x2 t2 = __builtin_shufflevector(t4, t4, 0, 1) + __builtin_shufflevector(t4, t4, 2, 3);
;     ps = t2.x + t2.y; }
;   { auto rr = __builtin_amdgcn_permlane32_swap(__float_as_uint(ps), __float_as_uint(ps), false, false);
;     ps = __uint_as_float(rr[0]) + __uint_as_float(rr[1]); }
;   l_reg = l_reg * alpha + ps;
; #pragma unroll
;   for (int w = 0; w < 4; ++w) { pa[w] = (int)pack4_fp8(p0[4 * w], p0[4 * w + 1], p0[4 * w + 2], p0[4 * w + 3]); pa[4 + w] = (int)pack4_fp8(p1[4 * w], p1[4 * w + 1], p1[4 * w + 2], p1[4 * w + 3]); }
; }
; template <int LDQ, int LDK, int LDO, int OSH>
; __device__ __forceinline__ void attn_body_f8(const unsigned char* Qb, const unsigned char* __restrict__ Kh, const unsigned char* __restrict__ VTh, long ldv, unsigned char* Ob, int seq, char* lds) {
;     ...
;     PV8(0, pa); partialSM8<5>(pB0, pB1, m_reg, mnB, alB);
;     __syncthreads(); SWAIT(); SWRITE(0, SE);
;     RESC(alB); __syncthreads();
;     SBAR(); qkt8(pA0, pA1, K_lds, q8, r32, hi);
;     finishSM8(pB0, pB1, alB, l_reg, pa); SBAR();
;     if (j + 3 < NT) SLOAD(SE, (j + 3) * KVBLK); SBAR();
.LBB0_369:
	v_cvt_pk_fp8_f32 v238, v186, v187
	v_cvt_pk_fp8_f32 v242, v196, v197
	v_cvt_pk_fp8_f32 v239, v182, v183
	v_cvt_pk_fp8_f32 v243, v194, v195
	v_cvt_pk_fp8_f32 v240, v184, v185
	v_cvt_pk_fp8_f32 v244, v204, v205
	v_cvt_pk_fp8_f32 v241, v180, v181
	v_cvt_pk_fp8_f32 v245, v202, v203
	v_cvt_pk_fp8_f32 v238, v148, v149 op_sel:[0,0,1]
	v_cvt_pk_fp8_f32 v242, v192, v193 op_sel:[0,0,1]
	v_cvt_pk_fp8_f32 v239, v152, v153 op_sel:[0,0,1]
	v_cvt_pk_fp8_f32 v243, v206, v207 op_sel:[0,0,1]
	v_cvt_pk_fp8_f32 v240, v146, v147 op_sel:[0,0,1]
	v_cvt_pk_fp8_f32 v244, v198, v199 op_sel:[0,0,1]
	v_cvt_pk_fp8_f32 v241, v150, v151 op_sel:[0,0,1]
	v_cvt_pk_fp8_f32 v245, v200, v201 op_sel:[0,0,1]
	s_waitcnt lgkmcnt(0)
	s_barrier
	v_mfma_scale_f32_32x32x64_f8f6f4 v[18:33], v[238:245], v[66:73], v[18:33], v216, v216 op_sel_hi:[0,0,0]
	s_waitcnt vmcnt(2)
	v_cmp_gt_f32_e32 vcc, 1.0, v237
	s_waitcnt vmcnt(2)
	ds_write_b128 v225, v[158:161]
	ds_write_b128 v226, v[154:157] offset:16384
	v_sub_f32_e32 v66, v97, v236
	v_sub_f32_e32 v67, v96, v236
	v_sub_f32_e32 v68, v95, v236
	v_sub_f32_e32 v69, v94, v236
	v_sub_f32_e32 v70, v93, v236
	v_sub_f32_e32 v71, v92, v236
	v_sub_f32_e32 v72, v91, v236
	v_sub_f32_e32 v73, v90, v236
	v_mfma_scale_f32_32x32x64_f8f6f4 v[34:49], v[238:245], v[74:81], v[34:49], v216, v216 op_sel_hi:[0,0,0]
	v_sub_f32_e32 v74, v89, v236
	v_sub_f32_e32 v75, v88, v236
	v_sub_f32_e32 v76, v87, v236
	v_sub_f32_e32 v77, v86, v236
	v_sub_f32_e32 v78, v85, v236
	v_sub_f32_e32 v79, v84, v236
	v_sub_f32_e32 v80, v83, v236
	v_sub_f32_e32 v81, v82, v236
	v_exp_f32_e32 v198, v81
	v_exp_f32_e32 v199, v80
	v_exp_f32_e32 v192, v79
	v_exp_f32_e32 v193, v78
	v_exp_f32_e32 v196, v77
	v_exp_f32_e32 v197, v76
	v_exp_f32_e32 v194, v75
	v_exp_f32_e32 v195, v74
	v_mfma_scale_f32_32x32x64_f8f6f4 v[2:17], v[238:245], v[138:145], v[2:17], v216, v216 op_sel_hi:[0,0,0]
	v_exp_f32_e32 v186, v73
	v_exp_f32_e32 v187, v72
	v_exp_f32_e32 v180, v71
	v_exp_f32_e32 v181, v70
	v_exp_f32_e32 v184, v69
	v_exp_f32_e32 v185, v68
	v_exp_f32_e32 v182, v67
	v_exp_f32_e32 v183, v66
	v_sub_f32_e32 v82, v113, v236
	v_sub_f32_e32 v83, v112, v236
	v_sub_f32_e32 v84, v111, v236
	v_sub_f32_e32 v85, v110, v236
	v_sub_f32_e32 v86, v109, v236
	v_sub_f32_e32 v87, v108, v236
	v_sub_f32_e32 v88, v107, v236
	v_sub_f32_e32 v89, v106, v236
	v_mfma_scale_f32_32x32x64_f8f6f4 v[50:65], v[238:245], v[130:137], v[50:65], v216, v216 op_sel_hi:[0,0,0]
	v_sub_f32_e32 v90, v105, v236
	v_sub_f32_e32 v91, v104, v236
	v_sub_f32_e32 v92, v103, v236
	v_sub_f32_e32 v93, v102, v236
	v_sub_f32_e32 v94, v101, v236
	v_sub_f32_e32 v95, v100, v236
	v_sub_f32_e32 v96, v99, v236
	v_sub_f32_e32 v97, v98, v236
	s_cbranch_vccz .LBB0_373
	s_nop 15
	s_and_saveexec_b64 s[8:9], s[2:3]
	ds_write_b32 v229, v237 offset:32896
	s_or_b64 exec, exec, s[8:9]
	s_waitcnt lgkmcnt(0)
	v_add_u32_e32 v78, v173, v228
	ds_read_b128 v[66:69], v78 offset:32992
	ds_read_b128 v[70:73], v78 offset:32960
	ds_read_b128 v[74:77], v78 offset:32928
	ds_read_b128 v[78:81], v78 offset:32896
	s_waitcnt lgkmcnt(3)
	s_nop 2
	v_pk_mul_f32 v[14:15], v[14:15], v[66:67]
	s_waitcnt lgkmcnt(2)
	v_pk_mul_f32 v[10:11], v[10:11], v[70:71]
	s_waitcnt lgkmcnt(1)
	v_pk_mul_f32 v[6:7], v[6:7], v[74:75]
	v_pk_mul_f32 v[16:17], v[16:17], v[68:69]
	v_pk_mul_f32 v[12:13], v[12:13], v[72:73]
	v_pk_mul_f32 v[8:9], v[8:9], v[76:77]
	s_waitcnt lgkmcnt(0)
	v_pk_mul_f32 v[4:5], v[4:5], v[80:81]
	v_pk_mul_f32 v[2:3], v[2:3], v[78:79]
	v_pk_mul_f32 v[62:63], v[62:63], v[66:67]
	v_pk_mul_f32 v[58:59], v[58:59], v[70:71]
	v_pk_mul_f32 v[54:55], v[54:55], v[74:75]
	v_pk_mul_f32 v[64:65], v[64:65], v[68:69]
	v_pk_mul_f32 v[60:61], v[60:61], v[72:73]
	v_pk_mul_f32 v[56:57], v[56:57], v[76:77]
	v_pk_mul_f32 v[52:53], v[52:53], v[80:81]
	v_pk_mul_f32 v[50:51], v[50:51], v[78:79]
	v_pk_mul_f32 v[46:47], v[46:47], v[66:67]
	v_pk_mul_f32 v[42:43], v[42:43], v[70:71]
	v_pk_mul_f32 v[38:39], v[38:39], v[74:75]
	v_pk_mul_f32 v[48:49], v[48:49], v[68:69]
	v_pk_mul_f32 v[44:45], v[44:45], v[72:73]
	v_pk_mul_f32 v[40:41], v[40:41], v[76:77]
	v_pk_mul_f32 v[36:37], v[36:37], v[80:81]
	v_pk_mul_f32 v[34:35], v[34:35], v[78:79]
	v_pk_mul_f32 v[30:31], v[30:31], v[66:67]
	v_pk_mul_f32 v[26:27], v[26:27], v[70:71]
	v_pk_mul_f32 v[22:23], v[22:23], v[74:75]
	v_pk_mul_f32 v[32:33], v[32:33], v[68:69]
	v_pk_mul_f32 v[28:29], v[28:29], v[72:73]
	v_pk_mul_f32 v[24:25], v[24:25], v[76:77]
	v_pk_mul_f32 v[20:21], v[20:21], v[80:81]
	v_pk_mul_f32 v[18:19], v[18:19], v[78:79]
.LBB0_373:
	s_waitcnt lgkmcnt(0)
	s_barrier
	ds_read_b128 v[66:69], v224 offset:4096
	ds_read_b128 v[74:77], v224
	ds_read_b128 v[70:73], v227 offset:4096
	ds_read_b128 v[78:81], v227
	ds_read_b128 v[102:105], v230 offset:4096
	ds_read_b128 v[130:133], v230
	ds_read_b128 v[106:109], v233 offset:4096
	ds_read_b128 v[134:137], v233
	v_exp_f32_e32 v212, v97
	v_exp_f32_e32 v213, v96
	v_exp_f32_e32 v206, v95
	v_exp_f32_e32 v207, v94
	v_exp_f32_e32 v210, v93
	v_exp_f32_e32 v211, v92
	v_exp_f32_e32 v208, v91
	v_exp_f32_e32 v209, v90
	v_exp_f32_e32 v204, v89
	v_exp_f32_e32 v205, v88
	v_exp_f32_e32 v112, v87
	v_exp_f32_e32 v113, v86
	v_exp_f32_e32 v202, v85
	v_exp_f32_e32 v200, v83
	v_exp_f32_e32 v201, v82
	v_exp_f32_e32 v203, v84
	v_pk_add_f32 v[82:83], v[112:113], v[180:181]
	v_pk_add_f32 v[84:85], v[206:207], v[192:193]
	v_pk_add_f32 v[86:87], v[200:201], v[182:183]
	v_pk_add_f32 v[88:89], v[208:209], v[194:195]
	v_pk_add_f32 v[90:91], v[204:205], v[186:187]
	v_pk_add_f32 v[92:93], v[212:213], v[198:199]
	v_pk_add_f32 v[94:95], v[202:203], v[184:185]
	v_pk_add_f32 v[96:97], v[210:211], v[196:197]
	v_pk_add_f32 v[90:91], v[92:93], v[90:91]
	v_pk_add_f32 v[94:95], v[96:97], v[94:95]
	v_pk_add_f32 v[86:87], v[88:89], v[86:87]
	v_pk_add_f32 v[82:83], v[84:85], v[82:83]
	v_pk_add_f32 v[84:85], v[90:91], v[94:95]
	v_pk_add_f32 v[82:83], v[82:83], v[86:87]
	s_nop 0
	v_pk_add_f32 v[82:83], v[84:85], v[82:83]
	s_nop 0
	v_pk_add_f32 v[110:111], v[82:83], v[82:83] op_sel:[0,1] op_sel_hi:[1,0]
	s_nop 0
	v_mov_b32_e32 v111, v110
	s_nop 1
	v_permlane32_swap_b32_e32 v110, v111
	s_cmp_ge_u32 s35, s34
	s_cselect_b64 s[8:9], -1, 0
	s_and_b64 vcc, exec, s[8:9]
	s_cbranch_vccnz .LBB0_375
	v_add_co_u32_e32 v82, vcc, 0x16310000, v190
	s_nop 1
	v_addc_co_u32_e32 v83, vcc, 0, v191, vcc
	v_add_co_u32_e32 v84, vcc, 0x16b00000, v188
	s_nop 1
	v_addc_co_u32_e32 v85, vcc, 0, v189, vcc
	global_load_dwordx4 v[158:161], v[82:83], off
	global_load_dwordx4 v[154:157], v[84:85], off offset:256
; #define SBAR() __builtin_amdgcn_sched_barrier(0)
; #define SLOAD(i, k0) do { sr_[i].vs0 = ld8(&Vh[(long)((k0) + sr) * LDK + sc]); sr_[i].vs1 = ld8(&Vh[(long)((k0) + 32 + sr) * LDK + sc]); \
;     sr_[i].ks0 = ld8(&Kh[(long)((k0) + sr) * LDK + sc]); sr_[i].ks1 = ld8(&Kh[(long)((k0) + 32 + sr) * LDK + sc]); } while (0)
; #define SWRITE(b, i) do { *(bf16x8*)((char*)V_lds + (b) * SHM_V + vst0) = sr_[i].vs0;          \
;     *(bf16x8*)((char*)V_lds + (b) * SHM_V + vst1) = sr_[i].vs1; int kc = sc * 2;               \
;     *(bf16x8*)((char*)K_lds + (b) * SHM_K + KSWZ(sr, kc)) = sr_[i].ks0;                       \
;     *(bf16x8*)((char*)K_lds + (b) * SHM_K + KSWZ(32 + sr, kc)) = sr_[i].ks1; } while (0)
; __device__ __forceinline__ void qkt8(f32x16& p0, f32x16& p1, const char* Ks, const i32x8* q8, int r32, int hi) {
;   const int g = (r32 >> 1) & 7;
;   const char* k0 = Ks + r32 * 128; const char* k1 = k0 + 32 * 128;
; #pragma unroll
;   for (int j = 0; j < 2; ++j) { const int c0 = 4 * j + 2 * hi;
;     const i32x8 a0 = F8_CAT(*(const i32x4*)(k0 + (((c0) ^ g) << 4)), *(const i32x4*)(k0 + (((c0 + 1) ^ g) << 4)));
;     const i32x8 a1 = F8_CAT(*(const i32x4*)(k1 + (((c0) ^ g) << 4)), *(const i32x4*)(k1 + (((c0 + 1) ^ g) << 4)));
;     if (j == 0) { p0 = F8_MFMA_QK(a0, q8[0], f32x16{}); p1 = F8_MFMA_QK(a1, q8[0], f32x16{}); }
;     else { p0 = F8_MFMA_QK(a0, q8[1], p0); p1 = F8_MFMA_QK(a1, q8[1], p1); } }
; }
; __device__ __forceinline__ void pv8(f32x16* o, const char* Vs, i32x8 pa, int r32, int hi) {
; #pragma unroll
;   for (int db = 0; db < 4; ++db) { const int d = 32 * db + r32, f = (d >> 2) & 3; const char* vr = Vs + d * 64;
;     const i32x8 b = F8_CAT(*(const i32x4*)(vr + (((2 * hi) ^ f) << 4)), *(const i32x4*)(vr + (((2 * hi + 1) ^ f) << 4)));
;     o[db] = F8_MFMA(pa, b, o[db]); }
; }
; template <int LDQ, int LDK, int LDO, int OSH>
; __device__ __forceinline__ void attn_body_f8(const unsigned char* Qb, const unsigned char* __restrict__ Kh, const unsigned char* __restrict__ VTh, long ldv, unsigned char* Ob, int seq, char* lds) {
;     ...
;     SBAR(); qkt8(pA0, pA1, K_lds, q8, r32, hi);
;     finishSM8(pB0, pB1, alB, l_reg, pa); SBAR();
;     if (j + 3 < NT) SLOAD(SE, (j + 3) * KVBLK); SBAR();
;     PV8(1, pa); partialSM8<5>(pA0, pA1, m_reg, mnA, alA);
;     __syncthreads(); SWAIT(); SWRITE(1, SO);
;     RESC(alA); __syncthreads();
.LBB0_375:
	s_waitcnt lgkmcnt(4)
	v_mfma_scale_f32_32x32x64_f8f6f4 v[86:101], v[74:81], v[122:129], 0, v216, v219 op_sel_hi:[0,0,0]
	v_mfma_scale_f32_32x32x64_f8f6f4 v[70:85], v[66:73], v[122:129], 0, v216, v219 op_sel_hi:[0,0,0]
	s_waitcnt lgkmcnt(0)
	v_mfma_scale_f32_32x32x64_f8f6f4 v[86:101], v[130:137], v[114:121], v[86:101], v216, v219 op_sel_hi:[0,0,0]
	v_mfma_scale_f32_32x32x64_f8f6f4 v[70:85], v[102:109], v[114:121], v[70:85], v216, v219 op_sel_hi:[0,0,0]
	v_cvt_pk_fp8_f32 v238, v198, v199
	v_cvt_pk_fp8_f32 v242, v212, v213
	v_cvt_pk_fp8_f32 v239, v196, v197
	v_cvt_pk_fp8_f32 v243, v210, v211
	v_cvt_pk_fp8_f32 v240, v186, v187
	v_cvt_pk_fp8_f32 v244, v204, v205
	v_cvt_pk_fp8_f32 v241, v184, v185
	v_cvt_pk_fp8_f32 v245, v202, v203
	v_cvt_pk_fp8_f32 v238, v192, v193 op_sel:[0,0,1]
	v_cvt_pk_fp8_f32 v242, v206, v207 op_sel:[0,0,1]
	v_cvt_pk_fp8_f32 v239, v194, v195 op_sel:[0,0,1]
	v_cvt_pk_fp8_f32 v243, v208, v209 op_sel:[0,0,1]
	v_cvt_pk_fp8_f32 v240, v180, v181 op_sel:[0,0,1]
	v_cvt_pk_fp8_f32 v244, v112, v113 op_sel:[0,0,1]
	v_cvt_pk_fp8_f32 v241, v182, v183 op_sel:[0,0,1]
	v_cvt_pk_fp8_f32 v245, v200, v201 op_sel:[0,0,1]
	s_nop 2
	v_max_f32_e32 v66, v86, v87
	v_max3_f32 v66, v66, v88, v89
	v_max3_f32 v66, v66, v90, v91
	v_max3_f32 v66, v66, v92, v93
	v_max3_f32 v66, v66, v94, v95
	v_max3_f32 v66, v66, v96, v97
	v_max3_f32 v66, v66, v98, v99
	v_max3_f32 v66, v66, v100, v101
	v_max3_f32 v66, v66, v70, v71
	v_max3_f32 v66, v66, v72, v73
	v_max3_f32 v66, v66, v74, v75
	s_waitcnt lgkmcnt(0)
	v_max3_f32 v66, v66, v76, v77
	ds_read_b128 v[146:149], v232 offset:24576
	ds_read_b128 v[138:141], v232 offset:26624
	ds_read_b128 v[150:153], v231 offset:24576
	ds_read_b128 v[142:145], v231 offset:26624
	ds_read_b128 v[130:133], v232 offset:28672
	ds_read_b128 v[102:105], v232 offset:30720
	ds_read_b128 v[134:137], v231 offset:28672
	ds_read_b128 v[106:109], v231 offset:30720
	v_max3_f32 v66, v66, v78, v79
	v_max3_f32 v66, v66, v80, v81
	v_max3_f32 v66, v66, v82, v83
	v_max3_f32 v66, v66, v84, v85
	v_mov_b32_e32 v67, v66
	s_nop 1
	v_permlane32_swap_b32_e32 v66, v67
	v_max_f32_e32 v66, v66, v67
	v_sub_f32_e32 v67, v66, v179
	v_cmp_ge_f32_e32 vcc, s37, v67
	s_cmp_eq_u64 vcc, exec
	s_cbranch_scc0 .LBB0_384
	v_mov_b32_e32 v188, 1.0
.LBB0_377:
	s_waitcnt lgkmcnt(0)
	s_barrier
	v_mfma_scale_f32_32x32x64_f8f6f4 v[2:17], v[238:245], v[146:153], v[2:17], v216, v216 op_sel_hi:[0,0,0]
	s_waitcnt vmcnt(2)
	v_cmp_gt_f32_e32 vcc, 1.0, v188
	s_waitcnt vmcnt(1)
	ds_write_b128 v225, v[162:165] offset:8192
	s_waitcnt vmcnt(0)
	ds_write_b128 v226, v[166:169] offset:24576
	v_sub_f32_e32 v66, v101, v236
	v_sub_f32_e32 v67, v100, v236
	v_sub_f32_e32 v68, v99, v236
	v_sub_f32_e32 v69, v98, v236
	v_sub_f32_e32 v97, v97, v236
	v_sub_f32_e32 v96, v96, v236
	v_sub_f32_e32 v95, v95, v236
	v_sub_f32_e32 v94, v94, v236
	v_mfma_scale_f32_32x32x64_f8f6f4 v[50:65], v[238:245], v[138:145], v[50:65], v216, v216 op_sel_hi:[0,0,0]
	v_sub_f32_e32 v93, v93, v236
	v_sub_f32_e32 v92, v92, v236
	v_sub_f32_e32 v91, v91, v236
	v_sub_f32_e32 v90, v90, v236
	v_sub_f32_e32 v89, v89, v236
	v_sub_f32_e32 v88, v88, v236
	v_sub_f32_e32 v87, v87, v236
	v_sub_f32_e32 v86, v86, v236
	v_exp_f32_e32 v186, v86
	v_exp_f32_e32 v187, v87
	v_exp_f32_e32 v148, v88
	v_exp_f32_e32 v149, v89
	v_exp_f32_e32 v182, v90
	v_exp_f32_e32 v183, v91
	v_exp_f32_e32 v152, v92
	v_exp_f32_e32 v153, v93
	v_mfma_scale_f32_32x32x64_f8f6f4 v[34:49], v[238:245], v[130:137], v[34:49], v216, v216 op_sel_hi:[0,0,0]
	v_exp_f32_e32 v184, v94
	v_exp_f32_e32 v185, v95
	v_exp_f32_e32 v146, v96
	v_exp_f32_e32 v147, v97
	v_exp_f32_e32 v180, v69
	v_exp_f32_e32 v181, v68
	v_exp_f32_e32 v150, v67
	v_exp_f32_e32 v151, v66
	v_sub_f32_e32 v68, v82, v236
	v_add_f32_e32 v82, v178, v235
	v_fmac_f32_e32 v82, v234, v0
	v_add_f32_e32 v0, v110, v111
	s_mov_b64 s[10:11], 0x8000
	v_sub_f32_e32 v67, v85, v236
	v_sub_f32_e32 v66, v84, v236
	v_sub_f32_e32 v69, v83, v236
	v_sub_f32_e32 v81, v81, v236
	v_sub_f32_e32 v80, v80, v236
	v_sub_f32_e32 v79, v79, v236
	v_sub_f32_e32 v78, v78, v236
	v_mfma_scale_f32_32x32x64_f8f6f4 v[18:33], v[238:245], v[102:109], v[18:33], v216, v216 op_sel_hi:[0,0,0]
	v_sub_f32_e32 v77, v77, v236
	v_sub_f32_e32 v76, v76, v236
	v_sub_f32_e32 v75, v75, v236
	v_sub_f32_e32 v74, v74, v236
	v_sub_f32_e32 v73, v73, v236
	v_sub_f32_e32 v72, v72, v236
	v_fmac_f32_e32 v0, v82, v237
	v_sub_f32_e32 v71, v71, v236
	v_sub_f32_e32 v70, v70, v236
	v_lshl_add_u64 v[174:175], v[174:175], 0, s[0:1]
	v_lshl_add_u64 v[176:177], v[176:177], 0, s[10:11]
	s_add_i32 s35, s35, 2
	s_cbranch_vccz .LBB0_381
	s_nop 15
	s_and_saveexec_b64 s[10:11], s[2:3]
	ds_write_b32 v229, v188 offset:32896
	s_or_b64 exec, exec, s[10:11]
	s_waitcnt lgkmcnt(0)
	v_add_u32_e32 v112, v173, v228
	ds_read_b128 v[138:141], v112 offset:32992
	ds_read_b128 v[102:105], v112 offset:32960
	ds_read_b128 v[106:109], v112 offset:32928
	ds_read_b128 v[130:133], v112 offset:32896
	s_waitcnt lgkmcnt(3)
	s_nop 1
	v_pk_mul_f32 v[14:15], v[14:15], v[138:139]
	s_waitcnt lgkmcnt(2)
	v_pk_mul_f32 v[10:11], v[10:11], v[102:103]
	s_waitcnt lgkmcnt(1)
	v_pk_mul_f32 v[6:7], v[6:7], v[106:107]
	v_pk_mul_f32 v[16:17], v[16:17], v[140:141]
	v_pk_mul_f32 v[12:13], v[12:13], v[104:105]
	v_pk_mul_f32 v[8:9], v[8:9], v[108:109]
	s_waitcnt lgkmcnt(0)
	v_pk_mul_f32 v[4:5], v[4:5], v[132:133]
	v_pk_mul_f32 v[2:3], v[2:3], v[130:131]
	v_pk_mul_f32 v[62:63], v[62:63], v[138:139]
	v_pk_mul_f32 v[58:59], v[58:59], v[102:103]
	v_pk_mul_f32 v[54:55], v[54:55], v[106:107]
	v_pk_mul_f32 v[64:65], v[64:65], v[140:141]
	v_pk_mul_f32 v[60:61], v[60:61], v[104:105]
	v_pk_mul_f32 v[56:57], v[56:57], v[108:109]
	v_pk_mul_f32 v[52:53], v[52:53], v[132:133]
	v_pk_mul_f32 v[50:51], v[50:51], v[130:131]
	v_pk_mul_f32 v[46:47], v[46:47], v[138:139]
	v_pk_mul_f32 v[42:43], v[42:43], v[102:103]
	v_pk_mul_f32 v[38:39], v[38:39], v[106:107]
	v_pk_mul_f32 v[48:49], v[48:49], v[140:141]
	v_pk_mul_f32 v[44:45], v[44:45], v[104:105]
	v_pk_mul_f32 v[40:41], v[40:41], v[108:109]
	v_pk_mul_f32 v[36:37], v[36:37], v[132:133]
	v_pk_mul_f32 v[34:35], v[34:35], v[130:131]
	v_pk_mul_f32 v[30:31], v[30:31], v[138:139]
	v_pk_mul_f32 v[26:27], v[26:27], v[102:103]
	v_pk_mul_f32 v[22:23], v[22:23], v[106:107]
	v_pk_mul_f32 v[32:33], v[32:33], v[140:141]
	v_pk_mul_f32 v[28:29], v[28:29], v[104:105]
	v_pk_mul_f32 v[24:25], v[24:25], v[108:109]
	v_pk_mul_f32 v[20:21], v[20:21], v[132:133]
	v_pk_mul_f32 v[18:19], v[18:19], v[130:131]
.LBB0_381:
	s_and_b64 vcc, exec, s[8:9]
	s_waitcnt lgkmcnt(0)
	s_barrier
	s_cbranch_vccnz .LBB0_385
	v_mov_b32_e32 v234, v188
	v_mov_b32_e32 v208, v179
	s_branch .LBB0_366
